# pipelined double-polling of the grid-barrier generation word (two staggered loads in flight, check-then-reissue)
# speedup vs baseline: 1.0012x; 1.0012x over previous
; __device__ __forceinline__ unsigned xb_ld(unsigned* p)              { return __hip_atomic_load(p, __ATOMIC_RELAXED, __HIP_MEMORY_SCOPE_AGENT); }
; __device__ __forceinline__ unsigned xb_add(unsigned* p, unsigned v) { return __hip_atomic_fetch_add(p, v, __ATOMIC_RELAXED, __HIP_MEMORY_SCOPE_AGENT); }
; #define XB_SPIN(cond, bar) do { unsigned _sp = 0; while (cond) { __builtin_amdgcn_s_sleep(1); \
;     if ((++_sp & 255u) == 0u) { if (xb_ld(&(bar)[XB_TMO])) break; if (_sp > XB_SPIN_CAP) { atomicAdd(&(bar)[XB_TMO], 1u); break; } } } } while (0)
; __device__ __forceinline__ void xcd_barrier(const XcdBarrier& b) {
;     ...
;         const unsigned old = xb_add(&bar[XB_XSUB(b.x)], 1u);
;         const unsigned gen = old / nloc;
;         if (old + 1u == (gen + 1u) * nloc) {
;             __builtin_amdgcn_fence(__ATOMIC_RELEASE, "agent");
;             asm volatile("s_waitcnt vmcnt(0)" ::: "memory");
;             const unsigned og = xb_add(&bar[XB_TOP], 1u);
;             const unsigned tg = og / nx;
;             if (og + 1u == (tg + 1u) * nx) xb_add(&bar[XB_TOPGEN], 1u);
;             else XB_SPIN(xb_ld(&bar[XB_TOPGEN]) == tg, bar);
;             __builtin_amdgcn_fence(__ATOMIC_ACQUIRE, "agent");
;             xb_add(&bar[XB_XGEN(b.x)], 1u);
;             asm volatile("s_waitcnt vmcnt(0)" ::: "memory");
;         } else {
;             XB_SPIN(xb_ld(&bar[XB_XGEN(b.x)]) == gen, bar);
.LBB0_51:
	s_or_b64 exec, exec, s[18:19]
	v_cvt_f32_u32_e32 v4, v2
	s_waitcnt vmcnt(0)
	v_readfirstlane_b32 s3, v3
	v_sub_u32_e32 v3, 0, v2
	v_rcp_iflag_f32_e32 v4, v4
	v_add_u32_e32 v5, s3, v1
	v_mul_f32_e32 v4, 0x4f7ffffe, v4
	v_cvt_u32_f32_e32 v4, v4
	v_mul_lo_u32 v1, v3, v4
	v_mul_hi_u32 v1, v4, v1
	v_add_u32_e32 v1, v4, v1
	v_mul_hi_u32 v1, v5, v1
	v_mul_lo_u32 v3, v1, v2
	v_sub_u32_e32 v3, v5, v3
	v_add_u32_e32 v4, 1, v1
	v_sub_u32_e32 v6, v3, v2
	v_cmp_ge_u32_e32 vcc, v3, v2
	s_nop 1
	v_cndmask_b32_e32 v1, v1, v4, vcc
	v_cndmask_b32_e32 v3, v3, v6, vcc
	v_add_u32_e32 v4, 1, v1
	v_cmp_ge_u32_e32 vcc, v3, v2
	v_add_u32_e32 v3, 1, v5
	s_nop 0
	v_cndmask_b32_e32 v1, v1, v4, vcc
	v_mul_lo_u32 v4, v2, v1
	v_add_u32_e32 v2, v4, v2
	v_cmp_ne_u32_e32 vcc, v3, v2
	s_and_saveexec_b64 s[16:17], vcc
	s_xor_b64 s[18:19], exec, s[16:17]
	s_cbranch_execz .LBB0_65
	s_waitcnt lgkmcnt(0)
	v_mov_b32_e32 v0, 0
	global_load_dword v2, v0, s[26:27] sc1
	s_waitcnt vmcnt(0)
	v_cmp_eq_u32_e32 vcc, v2, v1
	s_and_saveexec_b64 s[20:21], vcc
	s_cbranch_execz .LBB0_64
	s_mov_b32 s3, 1
	s_mov_b64 s[22:23], 0
	global_load_dword v250, v0, s[26:27] sc1
	s_sleep 16
	global_load_dword v251, v0, s[26:27] sc1
	s_branch .LBB0_55

; __device__ __forceinline__ unsigned xb_ld(unsigned* p)              { return __hip_atomic_load(p, __ATOMIC_RELAXED, __HIP_MEMORY_SCOPE_AGENT); }
; #define XB_SPIN(cond, bar) do { unsigned _sp = 0; while (cond) { __builtin_amdgcn_s_sleep(1); \
;     if ((++_sp & 255u) == 0u) { if (xb_ld(&(bar)[XB_TMO])) break; if (_sp > XB_SPIN_CAP) { atomicAdd(&(bar)[XB_TMO], 1u); break; } } } } while (0)
; __device__ __forceinline__ void xcd_barrier(const XcdBarrier& b) {
;     ...
;             XB_SPIN(xb_ld(&bar[XB_XGEN(b.x)]) == gen, bar);
.LBB0_57:
	s_waitcnt vmcnt(1)
	v_mov_b32_e32 v2, v250
	v_cmp_ne_u32_e32 vcc, v2, v1
	s_nop 1
	s_cbranch_vccnz .Ldp0
	global_load_dword v250, v0, s[26:27] sc1
	s_waitcnt vmcnt(1)
	v_mov_b32_e32 v2, v251
	v_cmp_ne_u32_e32 vcc, v2, v1
	s_nop 1
	s_cbranch_vccnz .Ldp0
	global_load_dword v251, v0, s[26:27] sc1
.Ldp0:
	s_add_i32 s3, s3, 1
	s_mov_b64 s[40:41], -1
	v_cmp_ne_u32_e32 vcc, v2, v1
	s_orn2_b64 s[38:39], vcc, exec
	s_branch .LBB0_54

; __device__ __forceinline__ unsigned xb_ld(unsigned* p)              { return __hip_atomic_load(p, __ATOMIC_RELAXED, __HIP_MEMORY_SCOPE_AGENT); }
; __device__ __forceinline__ unsigned xb_add(unsigned* p, unsigned v) { return __hip_atomic_fetch_add(p, v, __ATOMIC_RELAXED, __HIP_MEMORY_SCOPE_AGENT); }
; #define XB_SPIN(cond, bar) do { unsigned _sp = 0; while (cond) { __builtin_amdgcn_s_sleep(1); \
;     if ((++_sp & 255u) == 0u) { if (xb_ld(&(bar)[XB_TMO])) break; if (_sp > XB_SPIN_CAP) { atomicAdd(&(bar)[XB_TMO], 1u); break; } } } } while (0)
; __device__ __forceinline__ void xcd_barrier(const XcdBarrier& b) {
;     ...
;             const unsigned og = xb_add(&bar[XB_TOP], 1u);
;             const unsigned tg = og / nx;
;             if (og + 1u == (tg + 1u) * nx) xb_add(&bar[XB_TOPGEN], 1u);
;             else XB_SPIN(xb_ld(&bar[XB_TOPGEN]) == tg, bar);
.LBB0_68:
	s_or_b64 exec, exec, s[20:21]
	v_cvt_f32_u32_e32 v3, v0
	s_waitcnt vmcnt(0)
	v_readfirstlane_b32 s3, v2
	v_sub_u32_e32 v2, 0, v0
	s_mov_b64 s[20:21], -1
	v_rcp_iflag_f32_e32 v3, v3
	v_add_u32_e32 v1, s3, v1
	v_add_u32_e32 v4, 1, v1
	v_mul_f32_e32 v3, 0x4f7ffffe, v3
	v_cvt_u32_f32_e32 v3, v3
	v_mul_lo_u32 v2, v2, v3
	v_mul_hi_u32 v2, v3, v2
	v_add_u32_e32 v2, v3, v2
	v_mul_hi_u32 v2, v1, v2
	v_mul_lo_u32 v3, v2, v0
	v_sub_u32_e32 v1, v1, v3
	v_add_u32_e32 v5, 1, v2
	v_sub_u32_e32 v3, v1, v0
	v_cmp_ge_u32_e32 vcc, v1, v0
	s_nop 1
	v_cndmask_b32_e32 v2, v2, v5, vcc
	v_cndmask_b32_e32 v1, v1, v3, vcc
	v_add_u32_e32 v3, 1, v2
	v_cmp_ge_u32_e32 vcc, v1, v0
	s_nop 1
	v_cndmask_b32_e32 v2, v2, v3, vcc
	v_mul_lo_u32 v1, v0, v2
	v_add_u32_e32 v0, v1, v0
	v_cmp_ne_u32_e32 vcc, v4, v0
	v_mov_b64_e32 v[0:1], s[26:27]
	s_and_saveexec_b64 s[18:19], vcc
	s_cbranch_execz .LBB0_80
	v_mov_b32_e32 v0, 0
	global_load_dword v1, v0, s[26:27] sc1
	s_mov_b64 s[22:23], 0
	s_waitcnt vmcnt(0)
	v_cmp_eq_u32_e32 vcc, v1, v2
	s_and_saveexec_b64 s[20:21], vcc
	s_cbranch_execz .LBB0_79
	s_mov_b32 s3, 1
	global_load_dword v250, v0, s[26:27] sc1
	s_sleep 16
	global_load_dword v251, v0, s[26:27] sc1
	s_branch .LBB0_72

; __device__ __forceinline__ unsigned xb_ld(unsigned* p)              { return __hip_atomic_load(p, __ATOMIC_RELAXED, __HIP_MEMORY_SCOPE_AGENT); }
; #define XB_SPIN(cond, bar) do { unsigned _sp = 0; while (cond) { __builtin_amdgcn_s_sleep(1); \
;     if ((++_sp & 255u) == 0u) { if (xb_ld(&(bar)[XB_TMO])) break; if (_sp > XB_SPIN_CAP) { atomicAdd(&(bar)[XB_TMO], 1u); break; } } } } while (0)
; __device__ __forceinline__ void xcd_barrier(const XcdBarrier& b) {
;     ...
;             else XB_SPIN(xb_ld(&bar[XB_TOPGEN]) == tg, bar);
.LBB0_74:
	s_waitcnt vmcnt(1)
	v_mov_b32_e32 v1, v250
	v_cmp_ne_u32_e32 vcc, v1, v2
	s_nop 1
	s_cbranch_vccnz .Ldp1
	global_load_dword v250, v0, s[26:27] sc1
	s_waitcnt vmcnt(1)
	v_mov_b32_e32 v1, v251
	v_cmp_ne_u32_e32 vcc, v1, v2
	s_nop 1
	s_cbranch_vccnz .Ldp1
	global_load_dword v251, v0, s[26:27] sc1
.Ldp1:
	s_add_i32 s3, s3, 1
	s_mov_b64 s[38:39], -1
	v_cmp_ne_u32_e32 vcc, v1, v2
	s_orn2_b64 s[42:43], vcc, exec
	s_branch .LBB0_71

; __device__ __forceinline__ unsigned xb_ld(unsigned* p)              { return __hip_atomic_load(p, __ATOMIC_RELAXED, __HIP_MEMORY_SCOPE_AGENT); }
; __device__ __forceinline__ unsigned xb_add(unsigned* p, unsigned v) { return __hip_atomic_fetch_add(p, v, __ATOMIC_RELAXED, __HIP_MEMORY_SCOPE_AGENT); }
; #define XB_SPIN(cond, bar) do { unsigned _sp = 0; while (cond) { __builtin_amdgcn_s_sleep(1); \
;     if ((++_sp & 255u) == 0u) { if (xb_ld(&(bar)[XB_TMO])) break; if (_sp > XB_SPIN_CAP) { atomicAdd(&(bar)[XB_TMO], 1u); break; } } } } while (0)
; __device__ __forceinline__ void xcd_barrier(const XcdBarrier& b) {
;     ...
;         const unsigned old = xb_add(&bar[XB_XSUB(b.x)], 1u);
;         const unsigned gen = old / nloc;
;         if (old + 1u == (gen + 1u) * nloc) {
;             __builtin_amdgcn_fence(__ATOMIC_RELEASE, "agent");
;             asm volatile("s_waitcnt vmcnt(0)" ::: "memory");
;             const unsigned og = xb_add(&bar[XB_TOP], 1u);
;             const unsigned tg = og / nx;
;             if (og + 1u == (tg + 1u) * nx) xb_add(&bar[XB_TOPGEN], 1u);
;             else XB_SPIN(xb_ld(&bar[XB_TOPGEN]) == tg, bar);
;             __builtin_amdgcn_fence(__ATOMIC_ACQUIRE, "agent");
;             xb_add(&bar[XB_XGEN(b.x)], 1u);
;             asm volatile("s_waitcnt vmcnt(0)" ::: "memory");
;         } else {
;             XB_SPIN(xb_ld(&bar[XB_XGEN(b.x)]) == gen, bar);
.LBB0_182:
	s_or_b64 exec, exec, s[18:19]
	v_cvt_f32_u32_e32 v4, v2
	s_waitcnt vmcnt(0)
	v_readfirstlane_b32 s5, v3
	v_sub_u32_e32 v3, 0, v2
	v_rcp_iflag_f32_e32 v4, v4
	v_add_u32_e32 v5, s5, v1
	v_mul_f32_e32 v4, 0x4f7ffffe, v4
	v_cvt_u32_f32_e32 v4, v4
	v_mul_lo_u32 v1, v3, v4
	v_mul_hi_u32 v1, v4, v1
	v_add_u32_e32 v1, v4, v1
	v_mul_hi_u32 v1, v5, v1
	v_mul_lo_u32 v3, v1, v2
	v_sub_u32_e32 v3, v5, v3
	v_add_u32_e32 v4, 1, v1
	v_cmp_ge_u32_e32 vcc, v3, v2
	s_nop 1
	v_cndmask_b32_e32 v1, v1, v4, vcc
	v_sub_u32_e32 v4, v3, v2
	v_cndmask_b32_e32 v3, v3, v4, vcc
	v_add_u32_e32 v4, 1, v1
	v_cmp_ge_u32_e32 vcc, v3, v2
	v_add_u32_e32 v3, 1, v5
	s_nop 0
	v_cndmask_b32_e32 v1, v1, v4, vcc
	v_mul_lo_u32 v4, v2, v1
	v_add_u32_e32 v2, v4, v2
	v_cmp_ne_u32_e32 vcc, v3, v2
	s_and_saveexec_b64 s[14:15], vcc
	s_xor_b64 s[18:19], exec, s[14:15]
	s_cbranch_execz .LBB0_196
	s_waitcnt lgkmcnt(0)
	v_mov_b32_e32 v0, 0
	global_load_dword v2, v0, s[26:27] sc1
	s_waitcnt vmcnt(0)
	v_cmp_eq_u32_e32 vcc, v2, v1
	s_and_saveexec_b64 s[22:23], vcc
	s_cbranch_execz .LBB0_195
	s_mov_b32 s5, 1
	s_mov_b64 s[36:37], 0
	global_load_dword v250, v0, s[26:27] sc1
	s_sleep 16
	global_load_dword v251, v0, s[26:27] sc1
	s_branch .LBB0_186

; __device__ __forceinline__ unsigned xb_ld(unsigned* p)              { return __hip_atomic_load(p, __ATOMIC_RELAXED, __HIP_MEMORY_SCOPE_AGENT); }
; #define XB_SPIN(cond, bar) do { unsigned _sp = 0; while (cond) { __builtin_amdgcn_s_sleep(1); \
;     if ((++_sp & 255u) == 0u) { if (xb_ld(&(bar)[XB_TMO])) break; if (_sp > XB_SPIN_CAP) { atomicAdd(&(bar)[XB_TMO], 1u); break; } } } } while (0)
; __device__ __forceinline__ void xcd_barrier(const XcdBarrier& b) {
;     ...
;             XB_SPIN(xb_ld(&bar[XB_XGEN(b.x)]) == gen, bar);
.Ldp4:
	s_add_i32 s5, s5, 1
	s_mov_b64 s[42:43], -1
	v_cmp_ne_u32_e32 vcc, v2, v1
	s_orn2_b64 s[40:41], vcc, exec
	s_branch .LBB0_185

; __device__ __forceinline__ unsigned xb_ld(unsigned* p)              { return __hip_atomic_load(p, __ATOMIC_RELAXED, __HIP_MEMORY_SCOPE_AGENT); }
; __device__ __forceinline__ unsigned xb_add(unsigned* p, unsigned v) { return __hip_atomic_fetch_add(p, v, __ATOMIC_RELAXED, __HIP_MEMORY_SCOPE_AGENT); }
; #define XB_SPIN(cond, bar) do { unsigned _sp = 0; while (cond) { __builtin_amdgcn_s_sleep(1); \
;     if ((++_sp & 255u) == 0u) { if (xb_ld(&(bar)[XB_TMO])) break; if (_sp > XB_SPIN_CAP) { atomicAdd(&(bar)[XB_TMO], 1u); break; } } } } while (0)
; __device__ __forceinline__ void xcd_barrier(const XcdBarrier& b) {
;     ...
;             const unsigned og = xb_add(&bar[XB_TOP], 1u);
;             const unsigned tg = og / nx;
;             if (og + 1u == (tg + 1u) * nx) xb_add(&bar[XB_TOPGEN], 1u);
;             else XB_SPIN(xb_ld(&bar[XB_TOPGEN]) == tg, bar);
.LBB0_199:
	s_or_b64 exec, exec, s[22:23]
	s_waitcnt vmcnt(0)
	v_readfirstlane_b32 s5, v2
	v_cvt_f32_u32_e32 v2, v0
	v_sub_u32_e32 v3, 0, v0
	v_add_u32_e32 v1, s5, v1
	s_mov_b64 s[22:23], -1
	v_rcp_iflag_f32_e32 v2, v2
	s_nop 0
	v_mul_f32_e32 v2, 0x4f7ffffe, v2
	v_cvt_u32_f32_e32 v2, v2
	v_mul_lo_u32 v3, v3, v2
	v_mul_hi_u32 v3, v2, v3
	v_add_u32_e32 v2, v2, v3
	v_mul_hi_u32 v2, v1, v2
	v_mul_lo_u32 v3, v2, v0
	v_sub_u32_e32 v3, v1, v3
	v_cmp_ge_u32_e32 vcc, v3, v0
	v_add_u32_e32 v4, 1, v2
	v_add_u32_e32 v1, 1, v1
	v_cndmask_b32_e32 v2, v2, v4, vcc
	v_sub_u32_e32 v4, v3, v0
	v_cndmask_b32_e32 v3, v3, v4, vcc
	v_cmp_ge_u32_e32 vcc, v3, v0
	v_add_u32_e32 v3, 1, v2
	s_nop 0
	v_cndmask_b32_e32 v2, v2, v3, vcc
	v_mul_lo_u32 v3, v0, v2
	v_add_u32_e32 v0, v3, v0
	v_cmp_ne_u32_e32 vcc, v1, v0
	v_mov_b64_e32 v[0:1], s[26:27]
	s_and_saveexec_b64 s[18:19], vcc
	s_cbranch_execz .LBB0_211
	v_mov_b32_e32 v0, 0
	global_load_dword v1, v0, s[26:27] sc1
	s_mov_b64 s[36:37], 0
	s_waitcnt vmcnt(0)
	v_cmp_eq_u32_e32 vcc, v1, v2
	s_and_saveexec_b64 s[22:23], vcc
	s_cbranch_execz .LBB0_210
	s_mov_b32 s5, 1
	global_load_dword v250, v0, s[26:27] sc1
	s_sleep 16
	global_load_dword v251, v0, s[26:27] sc1
	s_branch .LBB0_203

; __device__ __forceinline__ unsigned xb_ld(unsigned* p)              { return __hip_atomic_load(p, __ATOMIC_RELAXED, __HIP_MEMORY_SCOPE_AGENT); }
; #define XB_SPIN(cond, bar) do { unsigned _sp = 0; while (cond) { __builtin_amdgcn_s_sleep(1); \
;     if ((++_sp & 255u) == 0u) { if (xb_ld(&(bar)[XB_TMO])) break; if (_sp > XB_SPIN_CAP) { atomicAdd(&(bar)[XB_TMO], 1u); break; } } } } while (0)
; __device__ __forceinline__ void xcd_barrier(const XcdBarrier& b) {
;     ...
;             else XB_SPIN(xb_ld(&bar[XB_TOPGEN]) == tg, bar);
.Ldp5:
	s_add_i32 s5, s5, 1
	s_mov_b64 s[40:41], -1
	v_cmp_ne_u32_e32 vcc, v1, v2
	s_orn2_b64 s[44:45], vcc, exec
	s_branch .LBB0_202

; __device__ __forceinline__ unsigned xb_ld(unsigned* p)              { return __hip_atomic_load(p, __ATOMIC_RELAXED, __HIP_MEMORY_SCOPE_AGENT); }
; __device__ __forceinline__ unsigned xb_add(unsigned* p, unsigned v) { return __hip_atomic_fetch_add(p, v, __ATOMIC_RELAXED, __HIP_MEMORY_SCOPE_AGENT); }
; #define XB_SPIN(cond, bar) do { unsigned _sp = 0; while (cond) { __builtin_amdgcn_s_sleep(1); \
;     if ((++_sp & 255u) == 0u) { if (xb_ld(&(bar)[XB_TMO])) break; if (_sp > XB_SPIN_CAP) { atomicAdd(&(bar)[XB_TMO], 1u); break; } } } } while (0)
; __device__ __forceinline__ void xcd_barrier(const XcdBarrier& b) {
;     ...
;         const unsigned old = xb_add(&bar[XB_XSUB(b.x)], 1u);
;         const unsigned gen = old / nloc;
;         if (old + 1u == (gen + 1u) * nloc) {
;             __builtin_amdgcn_fence(__ATOMIC_RELEASE, "agent");
;             asm volatile("s_waitcnt vmcnt(0)" ::: "memory");
;             const unsigned og = xb_add(&bar[XB_TOP], 1u);
;             const unsigned tg = og / nx;
;             if (og + 1u == (tg + 1u) * nx) xb_add(&bar[XB_TOPGEN], 1u);
;             else XB_SPIN(xb_ld(&bar[XB_TOPGEN]) == tg, bar);
;             __builtin_amdgcn_fence(__ATOMIC_ACQUIRE, "agent");
;             xb_add(&bar[XB_XGEN(b.x)], 1u);
;             asm volatile("s_waitcnt vmcnt(0)" ::: "memory");
;         } else {
;             XB_SPIN(xb_ld(&bar[XB_XGEN(b.x)]) == gen, bar);
.LBB0_493:
	s_or_b64 exec, exec, s[18:19]
	v_cvt_f32_u32_e32 v4, v2
	s_waitcnt vmcnt(0)
	v_readfirstlane_b32 s5, v3
	v_sub_u32_e32 v3, 0, v2
	v_rcp_iflag_f32_e32 v4, v4
	v_add_u32_e32 v5, s5, v1
	v_mul_f32_e32 v4, 0x4f7ffffe, v4
	v_cvt_u32_f32_e32 v4, v4
	v_mul_lo_u32 v1, v3, v4
	v_mul_hi_u32 v1, v4, v1
	v_add_u32_e32 v1, v4, v1
	v_mul_hi_u32 v1, v5, v1
	v_mul_lo_u32 v3, v1, v2
	v_sub_u32_e32 v3, v5, v3
	v_add_u32_e32 v4, 1, v1
	v_cmp_ge_u32_e32 vcc, v3, v2
	s_nop 1
	v_cndmask_b32_e32 v1, v1, v4, vcc
	v_sub_u32_e32 v4, v3, v2
	v_cndmask_b32_e32 v3, v3, v4, vcc
	v_add_u32_e32 v4, 1, v1
	v_cmp_ge_u32_e32 vcc, v3, v2
	v_add_u32_e32 v3, 1, v5
	s_nop 0
	v_cndmask_b32_e32 v1, v1, v4, vcc
	v_mul_lo_u32 v4, v2, v1
	v_add_u32_e32 v2, v4, v2
	v_cmp_ne_u32_e32 vcc, v3, v2
	s_and_saveexec_b64 s[14:15], vcc
	s_xor_b64 s[18:19], exec, s[14:15]
	s_cbranch_execz .LBB0_507
	s_waitcnt lgkmcnt(0)
	v_mov_b32_e32 v0, 0
	global_load_dword v2, v0, s[26:27] sc1
	s_waitcnt vmcnt(0)
	v_cmp_eq_u32_e32 vcc, v2, v1
	s_and_saveexec_b64 s[38:39], vcc
	s_cbranch_execz .LBB0_506
	s_mov_b32 s5, 1
	s_mov_b64 s[40:41], 0
	global_load_dword v250, v0, s[26:27] sc1
	s_sleep 16
	global_load_dword v251, v0, s[26:27] sc1
	s_branch .LBB0_497

; __device__ __forceinline__ unsigned xb_ld(unsigned* p)              { return __hip_atomic_load(p, __ATOMIC_RELAXED, __HIP_MEMORY_SCOPE_AGENT); }
; #define XB_SPIN(cond, bar) do { unsigned _sp = 0; while (cond) { __builtin_amdgcn_s_sleep(1); \
;     if ((++_sp & 255u) == 0u) { if (xb_ld(&(bar)[XB_TMO])) break; if (_sp > XB_SPIN_CAP) { atomicAdd(&(bar)[XB_TMO], 1u); break; } } } } while (0)
; __device__ __forceinline__ void xcd_barrier(const XcdBarrier& b) {
;     ...
;             XB_SPIN(xb_ld(&bar[XB_XGEN(b.x)]) == gen, bar);
.Ldp6:
	s_add_i32 s5, s5, 1
	s_mov_b64 s[46:47], -1
	v_cmp_ne_u32_e32 vcc, v2, v1
	s_orn2_b64 s[44:45], vcc, exec
	s_branch .LBB0_496

; __device__ __forceinline__ unsigned xb_ld(unsigned* p)              { return __hip_atomic_load(p, __ATOMIC_RELAXED, __HIP_MEMORY_SCOPE_AGENT); }
; __device__ __forceinline__ unsigned xb_add(unsigned* p, unsigned v) { return __hip_atomic_fetch_add(p, v, __ATOMIC_RELAXED, __HIP_MEMORY_SCOPE_AGENT); }
; #define XB_SPIN(cond, bar) do { unsigned _sp = 0; while (cond) { __builtin_amdgcn_s_sleep(1); \
;     if ((++_sp & 255u) == 0u) { if (xb_ld(&(bar)[XB_TMO])) break; if (_sp > XB_SPIN_CAP) { atomicAdd(&(bar)[XB_TMO], 1u); break; } } } } while (0)
; __device__ __forceinline__ void xcd_barrier(const XcdBarrier& b) {
;     ...
;             const unsigned og = xb_add(&bar[XB_TOP], 1u);
;             const unsigned tg = og / nx;
;             if (og + 1u == (tg + 1u) * nx) xb_add(&bar[XB_TOPGEN], 1u);
;             else XB_SPIN(xb_ld(&bar[XB_TOPGEN]) == tg, bar);
.LBB0_510:
	s_or_b64 exec, exec, s[38:39]
	s_waitcnt vmcnt(0)
	v_readfirstlane_b32 s5, v2
	v_cvt_f32_u32_e32 v2, v0
	v_sub_u32_e32 v3, 0, v0
	v_add_u32_e32 v1, s5, v1
	s_mov_b64 s[38:39], -1
	v_rcp_iflag_f32_e32 v2, v2
	s_nop 0
	v_mul_f32_e32 v2, 0x4f7ffffe, v2
	v_cvt_u32_f32_e32 v2, v2
	v_mul_lo_u32 v3, v3, v2
	v_mul_hi_u32 v3, v2, v3
	v_add_u32_e32 v2, v2, v3
	v_mul_hi_u32 v2, v1, v2
	v_mul_lo_u32 v3, v2, v0
	v_sub_u32_e32 v3, v1, v3
	v_cmp_ge_u32_e32 vcc, v3, v0
	v_add_u32_e32 v4, 1, v2
	v_add_u32_e32 v1, 1, v1
	v_cndmask_b32_e32 v2, v2, v4, vcc
	v_sub_u32_e32 v4, v3, v0
	v_cndmask_b32_e32 v3, v3, v4, vcc
	v_cmp_ge_u32_e32 vcc, v3, v0
	v_add_u32_e32 v3, 1, v2
	s_nop 0
	v_cndmask_b32_e32 v2, v2, v3, vcc
	v_mul_lo_u32 v3, v0, v2
	v_add_u32_e32 v0, v3, v0
	v_cmp_ne_u32_e32 vcc, v1, v0
	v_mov_b64_e32 v[0:1], s[26:27]
	s_and_saveexec_b64 s[18:19], vcc
	s_cbranch_execz .LBB0_522
	v_mov_b32_e32 v0, 0
	global_load_dword v1, v0, s[26:27] sc1
	s_mov_b64 s[40:41], 0
	s_waitcnt vmcnt(0)
	v_cmp_eq_u32_e32 vcc, v1, v2
	s_and_saveexec_b64 s[38:39], vcc
	s_cbranch_execz .LBB0_521
	s_mov_b32 s5, 1
	global_load_dword v250, v0, s[26:27] sc1
	s_sleep 16
	global_load_dword v251, v0, s[26:27] sc1
	s_branch .LBB0_514

; __device__ __forceinline__ unsigned xb_ld(unsigned* p)              { return __hip_atomic_load(p, __ATOMIC_RELAXED, __HIP_MEMORY_SCOPE_AGENT); }
; #define XB_SPIN(cond, bar) do { unsigned _sp = 0; while (cond) { __builtin_amdgcn_s_sleep(1); \
;     if ((++_sp & 255u) == 0u) { if (xb_ld(&(bar)[XB_TMO])) break; if (_sp > XB_SPIN_CAP) { atomicAdd(&(bar)[XB_TMO], 1u); break; } } } } while (0)
; __device__ __forceinline__ void xcd_barrier(const XcdBarrier& b) {
;     ...
;             else XB_SPIN(xb_ld(&bar[XB_TOPGEN]) == tg, bar);
.Ldp7:
	s_add_i32 s5, s5, 1
	s_mov_b64 s[44:45], -1
	v_cmp_ne_u32_e32 vcc, v1, v2
	s_orn2_b64 s[48:49], vcc, exec
	s_branch .LBB0_513

; __device__ __forceinline__ unsigned xb_ld(unsigned* p)              { return __hip_atomic_load(p, __ATOMIC_RELAXED, __HIP_MEMORY_SCOPE_AGENT); }
; __device__ __forceinline__ unsigned xb_add(unsigned* p, unsigned v) { return __hip_atomic_fetch_add(p, v, __ATOMIC_RELAXED, __HIP_MEMORY_SCOPE_AGENT); }
; #define XB_SPIN(cond, bar) do { unsigned _sp = 0; while (cond) { __builtin_amdgcn_s_sleep(1); \
;     if ((++_sp & 255u) == 0u) { if (xb_ld(&(bar)[XB_TMO])) break; if (_sp > XB_SPIN_CAP) { atomicAdd(&(bar)[XB_TMO], 1u); break; } } } } while (0)
; __device__ __forceinline__ void xcd_barrier(const XcdBarrier& b) {
;     ...
;         const unsigned old = xb_add(&bar[XB_XSUB(b.x)], 1u);
;         const unsigned gen = old / nloc;
;         if (old + 1u == (gen + 1u) * nloc) {
;             __builtin_amdgcn_fence(__ATOMIC_RELEASE, "agent");
;             asm volatile("s_waitcnt vmcnt(0)" ::: "memory");
;             const unsigned og = xb_add(&bar[XB_TOP], 1u);
;             const unsigned tg = og / nx;
;             if (og + 1u == (tg + 1u) * nx) xb_add(&bar[XB_TOPGEN], 1u);
;             else XB_SPIN(xb_ld(&bar[XB_TOPGEN]) == tg, bar);
;             __builtin_amdgcn_fence(__ATOMIC_ACQUIRE, "agent");
;             xb_add(&bar[XB_XGEN(b.x)], 1u);
;             asm volatile("s_waitcnt vmcnt(0)" ::: "memory");
;         } else {
;             XB_SPIN(xb_ld(&bar[XB_XGEN(b.x)]) == gen, bar);
.LBB0_583:
	s_or_b64 exec, exec, s[18:19]
	v_cvt_f32_u32_e32 v4, v2
	s_waitcnt vmcnt(0)
	v_readfirstlane_b32 s5, v3
	v_sub_u32_e32 v3, 0, v2
	v_rcp_iflag_f32_e32 v4, v4
	v_add_u32_e32 v5, s5, v1
	v_mul_f32_e32 v4, 0x4f7ffffe, v4
	v_cvt_u32_f32_e32 v4, v4
	v_mul_lo_u32 v1, v3, v4
	v_mul_hi_u32 v1, v4, v1
	v_add_u32_e32 v1, v4, v1
	v_mul_hi_u32 v1, v5, v1
	v_mul_lo_u32 v3, v1, v2
	v_sub_u32_e32 v3, v5, v3
	v_add_u32_e32 v4, 1, v1
	v_cmp_ge_u32_e32 vcc, v3, v2
	s_nop 1
	v_cndmask_b32_e32 v1, v1, v4, vcc
	v_sub_u32_e32 v4, v3, v2
	v_cndmask_b32_e32 v3, v3, v4, vcc
	v_add_u32_e32 v4, 1, v1
	v_cmp_ge_u32_e32 vcc, v3, v2
	v_add_u32_e32 v3, 1, v5
	s_nop 0
	v_cndmask_b32_e32 v1, v1, v4, vcc
	v_mul_lo_u32 v4, v2, v1
	v_add_u32_e32 v2, v4, v2
	v_cmp_ne_u32_e32 vcc, v3, v2
	s_and_saveexec_b64 s[14:15], vcc
	s_xor_b64 s[18:19], exec, s[14:15]
	s_cbranch_execz .LBB0_597
	s_waitcnt lgkmcnt(0)
	v_mov_b32_e32 v0, 0
	global_load_dword v2, v0, s[26:27] sc1
	s_waitcnt vmcnt(0)
	v_cmp_eq_u32_e32 vcc, v2, v1
	s_and_saveexec_b64 s[36:37], vcc
	s_cbranch_execz .LBB0_596
	s_mov_b32 s5, 1
	s_mov_b64 s[38:39], 0
	global_load_dword v250, v0, s[26:27] sc1
	s_sleep 16
	global_load_dword v251, v0, s[26:27] sc1
	s_branch .LBB0_587

; __device__ __forceinline__ unsigned xb_ld(unsigned* p)              { return __hip_atomic_load(p, __ATOMIC_RELAXED, __HIP_MEMORY_SCOPE_AGENT); }
; __device__ __forceinline__ unsigned xb_add(unsigned* p, unsigned v) { return __hip_atomic_fetch_add(p, v, __ATOMIC_RELAXED, __HIP_MEMORY_SCOPE_AGENT); }
; #define XB_SPIN(cond, bar) do { unsigned _sp = 0; while (cond) { __builtin_amdgcn_s_sleep(1); \
;     if ((++_sp & 255u) == 0u) { if (xb_ld(&(bar)[XB_TMO])) break; if (_sp > XB_SPIN_CAP) { atomicAdd(&(bar)[XB_TMO], 1u); break; } } } } while (0)
; __device__ __forceinline__ void xcd_barrier(const XcdBarrier& b) {
;     ...
;             const unsigned og = xb_add(&bar[XB_TOP], 1u);
;             const unsigned tg = og / nx;
;             if (og + 1u == (tg + 1u) * nx) xb_add(&bar[XB_TOPGEN], 1u);
;             else XB_SPIN(xb_ld(&bar[XB_TOPGEN]) == tg, bar);
.LBB0_600:
	s_or_b64 exec, exec, s[36:37]
	s_waitcnt vmcnt(0)
	v_readfirstlane_b32 s5, v2
	v_cvt_f32_u32_e32 v2, v0
	v_sub_u32_e32 v3, 0, v0
	v_add_u32_e32 v1, s5, v1
	s_mov_b64 s[36:37], -1
	v_rcp_iflag_f32_e32 v2, v2
	s_nop 0
	v_mul_f32_e32 v2, 0x4f7ffffe, v2
	v_cvt_u32_f32_e32 v2, v2
	v_mul_lo_u32 v3, v3, v2
	v_mul_hi_u32 v3, v2, v3
	v_add_u32_e32 v2, v2, v3
	v_mul_hi_u32 v2, v1, v2
	v_mul_lo_u32 v3, v2, v0
	v_sub_u32_e32 v3, v1, v3
	v_cmp_ge_u32_e32 vcc, v3, v0
	v_add_u32_e32 v4, 1, v2
	v_add_u32_e32 v1, 1, v1
	v_cndmask_b32_e32 v2, v2, v4, vcc
	v_sub_u32_e32 v4, v3, v0
	v_cndmask_b32_e32 v3, v3, v4, vcc
	v_cmp_ge_u32_e32 vcc, v3, v0
	v_add_u32_e32 v3, 1, v2
	s_nop 0
	v_cndmask_b32_e32 v2, v2, v3, vcc
	v_mul_lo_u32 v3, v0, v2
	v_add_u32_e32 v0, v3, v0
	v_cmp_ne_u32_e32 vcc, v1, v0
	v_mov_b64_e32 v[0:1], s[26:27]
	s_and_saveexec_b64 s[18:19], vcc
	s_cbranch_execz .LBB0_612
	v_mov_b32_e32 v0, 0
	global_load_dword v1, v0, s[26:27] sc1
	s_mov_b64 s[38:39], 0
	s_waitcnt vmcnt(0)
	v_cmp_eq_u32_e32 vcc, v1, v2
	s_and_saveexec_b64 s[36:37], vcc
	s_cbranch_execz .LBB0_611
	s_mov_b32 s5, 1
	global_load_dword v250, v0, s[26:27] sc1
	s_sleep 16
	global_load_dword v251, v0, s[26:27] sc1
	s_branch .LBB0_604

; __device__ __forceinline__ unsigned xb_ld(unsigned* p)              { return __hip_atomic_load(p, __ATOMIC_RELAXED, __HIP_MEMORY_SCOPE_AGENT); }
; __device__ __forceinline__ unsigned xb_add(unsigned* p, unsigned v) { return __hip_atomic_fetch_add(p, v, __ATOMIC_RELAXED, __HIP_MEMORY_SCOPE_AGENT); }
; #define XB_SPIN(cond, bar) do { unsigned _sp = 0; while (cond) { __builtin_amdgcn_s_sleep(1); \
;     if ((++_sp & 255u) == 0u) { if (xb_ld(&(bar)[XB_TMO])) break; if (_sp > XB_SPIN_CAP) { atomicAdd(&(bar)[XB_TMO], 1u); break; } } } } while (0)
; __device__ __forceinline__ void xcd_barrier(const XcdBarrier& b) {
;     ...
;         const unsigned old = xb_add(&bar[XB_XSUB(b.x)], 1u);
;         const unsigned gen = old / nloc;
;         if (old + 1u == (gen + 1u) * nloc) {
;             __builtin_amdgcn_fence(__ATOMIC_RELEASE, "agent");
;             asm volatile("s_waitcnt vmcnt(0)" ::: "memory");
;             const unsigned og = xb_add(&bar[XB_TOP], 1u);
;             const unsigned tg = og / nx;
;             if (og + 1u == (tg + 1u) * nx) xb_add(&bar[XB_TOPGEN], 1u);
;             else XB_SPIN(xb_ld(&bar[XB_TOPGEN]) == tg, bar);
;             __builtin_amdgcn_fence(__ATOMIC_ACQUIRE, "agent");
;             xb_add(&bar[XB_XGEN(b.x)], 1u);
;             asm volatile("s_waitcnt vmcnt(0)" ::: "memory");
;         } else {
;             XB_SPIN(xb_ld(&bar[XB_XGEN(b.x)]) == gen, bar);
.LBB0_770:
	s_or_b64 exec, exec, s[4:5]
	v_cvt_f32_u32_e32 v4, v2
	s_waitcnt vmcnt(0)
	v_readfirstlane_b32 s4, v3
	v_sub_u32_e32 v3, 0, v2
	v_rcp_iflag_f32_e32 v4, v4
	v_add_u32_e32 v5, s4, v1
	v_mul_f32_e32 v4, 0x4f7ffffe, v4
	v_cvt_u32_f32_e32 v4, v4
	v_mul_lo_u32 v1, v3, v4
	v_mul_hi_u32 v1, v4, v1
	v_add_u32_e32 v1, v4, v1
	v_mul_hi_u32 v1, v5, v1
	v_mul_lo_u32 v3, v1, v2
	v_sub_u32_e32 v3, v5, v3
	v_add_u32_e32 v4, 1, v1
	v_cmp_ge_u32_e32 vcc, v3, v2
	s_nop 1
	v_cndmask_b32_e32 v1, v1, v4, vcc
	v_sub_u32_e32 v4, v3, v2
	v_cndmask_b32_e32 v3, v3, v4, vcc
	v_add_u32_e32 v4, 1, v1
	v_cmp_ge_u32_e32 vcc, v3, v2
	v_add_u32_e32 v3, 1, v5
	s_nop 0
	v_cndmask_b32_e32 v1, v1, v4, vcc
	v_mul_lo_u32 v4, v2, v1
	v_add_u32_e32 v2, v4, v2
	v_cmp_ne_u32_e32 vcc, v3, v2
	s_and_saveexec_b64 s[4:5], vcc
	s_xor_b64 s[4:5], exec, s[4:5]
	s_cbranch_execz .LBB0_784
	s_waitcnt lgkmcnt(0)
	v_mov_b32_e32 v0, 0
	global_load_dword v2, v0, s[26:27] sc1
	s_waitcnt vmcnt(0)
	v_cmp_eq_u32_e32 vcc, v2, v1
	s_and_saveexec_b64 s[18:19], vcc
	s_cbranch_execz .LBB0_783
	s_mov_b32 s16, 1
	s_mov_b64 s[36:37], 0
	global_load_dword v250, v0, s[26:27] sc1
	s_sleep 16
	global_load_dword v251, v0, s[26:27] sc1
	s_branch .LBB0_774

; __device__ __forceinline__ unsigned xb_ld(unsigned* p)              { return __hip_atomic_load(p, __ATOMIC_RELAXED, __HIP_MEMORY_SCOPE_AGENT); }
; #define XB_SPIN(cond, bar) do { unsigned _sp = 0; while (cond) { __builtin_amdgcn_s_sleep(1); \
;     if ((++_sp & 255u) == 0u) { if (xb_ld(&(bar)[XB_TMO])) break; if (_sp > XB_SPIN_CAP) { atomicAdd(&(bar)[XB_TMO], 1u); break; } } } } while (0)
; __device__ __forceinline__ void xcd_barrier(const XcdBarrier& b) {
;     ...
;             XB_SPIN(xb_ld(&bar[XB_XGEN(b.x)]) == gen, bar);
.Ldp10:
	s_add_i32 s16, s16, 1
	s_mov_b64 s[42:43], -1
	v_cmp_ne_u32_e32 vcc, v2, v1
	s_orn2_b64 s[40:41], vcc, exec
	s_branch .LBB0_773

; __device__ __forceinline__ unsigned xb_ld(unsigned* p)              { return __hip_atomic_load(p, __ATOMIC_RELAXED, __HIP_MEMORY_SCOPE_AGENT); }
; __device__ __forceinline__ unsigned xb_add(unsigned* p, unsigned v) { return __hip_atomic_fetch_add(p, v, __ATOMIC_RELAXED, __HIP_MEMORY_SCOPE_AGENT); }
; #define XB_SPIN(cond, bar) do { unsigned _sp = 0; while (cond) { __builtin_amdgcn_s_sleep(1); \
;     if ((++_sp & 255u) == 0u) { if (xb_ld(&(bar)[XB_TMO])) break; if (_sp > XB_SPIN_CAP) { atomicAdd(&(bar)[XB_TMO], 1u); break; } } } } while (0)
; __device__ __forceinline__ void xcd_barrier(const XcdBarrier& b) {
;     ...
;             const unsigned og = xb_add(&bar[XB_TOP], 1u);
;             const unsigned tg = og / nx;
;             if (og + 1u == (tg + 1u) * nx) xb_add(&bar[XB_TOPGEN], 1u);
;             else XB_SPIN(xb_ld(&bar[XB_TOPGEN]) == tg, bar);
.LBB0_787:
	s_or_b64 exec, exec, s[18:19]
	s_waitcnt vmcnt(0)
	v_readfirstlane_b32 s4, v2
	v_cvt_f32_u32_e32 v2, v0
	v_sub_u32_e32 v3, 0, v0
	v_add_u32_e32 v1, s4, v1
	s_mov_b64 s[18:19], -1
	v_rcp_iflag_f32_e32 v2, v2
	s_nop 0
	v_mul_f32_e32 v2, 0x4f7ffffe, v2
	v_cvt_u32_f32_e32 v2, v2
	v_mul_lo_u32 v3, v3, v2
	v_mul_hi_u32 v3, v2, v3
	v_add_u32_e32 v2, v2, v3
	v_mul_hi_u32 v2, v1, v2
	v_mul_lo_u32 v3, v2, v0
	v_sub_u32_e32 v3, v1, v3
	v_cmp_ge_u32_e32 vcc, v3, v0
	v_add_u32_e32 v4, 1, v2
	v_add_u32_e32 v1, 1, v1
	v_cndmask_b32_e32 v2, v2, v4, vcc
	v_sub_u32_e32 v4, v3, v0
	v_cndmask_b32_e32 v3, v3, v4, vcc
	v_cmp_ge_u32_e32 vcc, v3, v0
	v_add_u32_e32 v3, 1, v2
	s_nop 0
	v_cndmask_b32_e32 v2, v2, v3, vcc
	v_mul_lo_u32 v3, v0, v2
	v_add_u32_e32 v0, v3, v0
	v_cmp_ne_u32_e32 vcc, v1, v0
	v_mov_b64_e32 v[0:1], s[26:27]
	s_and_saveexec_b64 s[4:5], vcc
	s_cbranch_execz .LBB0_799
	v_mov_b32_e32 v0, 0
	global_load_dword v1, v0, s[26:27] sc1
	s_mov_b64 s[36:37], 0
	s_waitcnt vmcnt(0)
	v_cmp_eq_u32_e32 vcc, v1, v2
	s_and_saveexec_b64 s[18:19], vcc
	s_cbranch_execz .LBB0_798
	s_mov_b32 s16, 1
	global_load_dword v250, v0, s[26:27] sc1
	s_sleep 16
	global_load_dword v251, v0, s[26:27] sc1
	s_branch .LBB0_791

; __device__ __forceinline__ unsigned xb_ld(unsigned* p)              { return __hip_atomic_load(p, __ATOMIC_RELAXED, __HIP_MEMORY_SCOPE_AGENT); }
; #define XB_SPIN(cond, bar) do { unsigned _sp = 0; while (cond) { __builtin_amdgcn_s_sleep(1); \
;     if ((++_sp & 255u) == 0u) { if (xb_ld(&(bar)[XB_TMO])) break; if (_sp > XB_SPIN_CAP) { atomicAdd(&(bar)[XB_TMO], 1u); break; } } } } while (0)
; __device__ __forceinline__ void xcd_barrier(const XcdBarrier& b) {
;     ...
;             else XB_SPIN(xb_ld(&bar[XB_TOPGEN]) == tg, bar);
.Ldp11:
	s_add_i32 s16, s16, 1
	s_mov_b64 s[40:41], -1
	v_cmp_ne_u32_e32 vcc, v1, v2
	s_orn2_b64 s[44:45], vcc, exec
	s_branch .LBB0_790

; __device__ __forceinline__ unsigned xb_ld(unsigned* p)              { return __hip_atomic_load(p, __ATOMIC_RELAXED, __HIP_MEMORY_SCOPE_AGENT); }
; __device__ __forceinline__ unsigned xb_add(unsigned* p, unsigned v) { return __hip_atomic_fetch_add(p, v, __ATOMIC_RELAXED, __HIP_MEMORY_SCOPE_AGENT); }
; #define XB_SPIN(cond, bar) do { unsigned _sp = 0; while (cond) { __builtin_amdgcn_s_sleep(1); \
;     if ((++_sp & 255u) == 0u) { if (xb_ld(&(bar)[XB_TMO])) break; if (_sp > XB_SPIN_CAP) { atomicAdd(&(bar)[XB_TMO], 1u); break; } } } } while (0)
; __device__ __forceinline__ void xcd_barrier(const XcdBarrier& b) {
;     ...
;         const unsigned old = xb_add(&bar[XB_XSUB(b.x)], 1u);
;         const unsigned gen = old / nloc;
;         if (old + 1u == (gen + 1u) * nloc) {
;             __builtin_amdgcn_fence(__ATOMIC_RELEASE, "agent");
;             asm volatile("s_waitcnt vmcnt(0)" ::: "memory");
;             const unsigned og = xb_add(&bar[XB_TOP], 1u);
;             const unsigned tg = og / nx;
;             if (og + 1u == (tg + 1u) * nx) xb_add(&bar[XB_TOPGEN], 1u);
;             else XB_SPIN(xb_ld(&bar[XB_TOPGEN]) == tg, bar);
;             __builtin_amdgcn_fence(__ATOMIC_ACQUIRE, "agent");
;             xb_add(&bar[XB_XGEN(b.x)], 1u);
;             asm volatile("s_waitcnt vmcnt(0)" ::: "memory");
;         } else {
;             XB_SPIN(xb_ld(&bar[XB_XGEN(b.x)]) == gen, bar);
.LBB0_944:
	s_or_b64 exec, exec, s[4:5]
	v_cvt_f32_u32_e32 v4, v2
	s_waitcnt vmcnt(0)
	v_readfirstlane_b32 s4, v3
	v_sub_u32_e32 v3, 0, v2
	v_rcp_iflag_f32_e32 v4, v4
	v_add_u32_e32 v5, s4, v1
	v_mul_f32_e32 v4, 0x4f7ffffe, v4
	v_cvt_u32_f32_e32 v4, v4
	v_mul_lo_u32 v1, v3, v4
	v_mul_hi_u32 v1, v4, v1
	v_add_u32_e32 v1, v4, v1
	v_mul_hi_u32 v1, v5, v1
	v_mul_lo_u32 v3, v1, v2
	v_sub_u32_e32 v3, v5, v3
	v_add_u32_e32 v4, 1, v1
	v_cmp_ge_u32_e32 vcc, v3, v2
	s_nop 1
	v_cndmask_b32_e32 v1, v1, v4, vcc
	v_sub_u32_e32 v4, v3, v2
	v_cndmask_b32_e32 v3, v3, v4, vcc
	v_add_u32_e32 v4, 1, v1
	v_cmp_ge_u32_e32 vcc, v3, v2
	v_add_u32_e32 v3, 1, v5
	s_nop 0
	v_cndmask_b32_e32 v1, v1, v4, vcc
	v_mul_lo_u32 v4, v2, v1
	v_add_u32_e32 v2, v4, v2
	v_cmp_ne_u32_e32 vcc, v3, v2
	s_and_saveexec_b64 s[4:5], vcc
	s_xor_b64 s[4:5], exec, s[4:5]
	s_cbranch_execz .LBB0_958
	s_waitcnt lgkmcnt(0)
	v_mov_b32_e32 v0, 0
	global_load_dword v2, v0, s[26:27] sc1
	s_waitcnt vmcnt(0)
	v_cmp_eq_u32_e32 vcc, v2, v1
	s_and_saveexec_b64 s[14:15], vcc
	s_cbranch_execz .LBB0_957
	s_mov_b64 s[28:29], s[26:27]
	s_mov_b32 s26, 1
	s_mov_b64 s[16:17], 0
	global_load_dword v250, v0, s[28:29] sc1
	s_sleep 16
	global_load_dword v251, v0, s[28:29] sc1
	s_branch .LBB0_948

; __device__ __forceinline__ unsigned xb_ld(unsigned* p)              { return __hip_atomic_load(p, __ATOMIC_RELAXED, __HIP_MEMORY_SCOPE_AGENT); }
; #define XB_SPIN(cond, bar) do { unsigned _sp = 0; while (cond) { __builtin_amdgcn_s_sleep(1); \
;     if ((++_sp & 255u) == 0u) { if (xb_ld(&(bar)[XB_TMO])) break; if (_sp > XB_SPIN_CAP) { atomicAdd(&(bar)[XB_TMO], 1u); break; } } } } while (0)
; __device__ __forceinline__ void xcd_barrier(const XcdBarrier& b) {
;     ...
;             XB_SPIN(xb_ld(&bar[XB_XGEN(b.x)]) == gen, bar);
.LBB0_950:
	s_waitcnt vmcnt(1)
	v_mov_b32_e32 v2, v250
	v_cmp_ne_u32_e32 vcc, v2, v1
	s_nop 1
	s_cbranch_vccnz .Ldp12
	global_load_dword v250, v0, s[28:29] sc1
	s_waitcnt vmcnt(1)
	v_mov_b32_e32 v2, v251
	v_cmp_ne_u32_e32 vcc, v2, v1
	s_nop 1
	s_cbranch_vccnz .Ldp12
	global_load_dword v251, v0, s[28:29] sc1
.Ldp12:
	s_add_i32 s26, s26, 1
	s_mov_b64 s[22:23], -1
	v_cmp_ne_u32_e32 vcc, v2, v1
	s_orn2_b64 s[20:21], vcc, exec
	s_branch .LBB0_947

; __device__ __forceinline__ unsigned xb_ld(unsigned* p)              { return __hip_atomic_load(p, __ATOMIC_RELAXED, __HIP_MEMORY_SCOPE_AGENT); }
; __device__ __forceinline__ unsigned xb_add(unsigned* p, unsigned v) { return __hip_atomic_fetch_add(p, v, __ATOMIC_RELAXED, __HIP_MEMORY_SCOPE_AGENT); }
; #define XB_SPIN(cond, bar) do { unsigned _sp = 0; while (cond) { __builtin_amdgcn_s_sleep(1); \
;     if ((++_sp & 255u) == 0u) { if (xb_ld(&(bar)[XB_TMO])) break; if (_sp > XB_SPIN_CAP) { atomicAdd(&(bar)[XB_TMO], 1u); break; } } } } while (0)
; __device__ __forceinline__ void xcd_barrier(const XcdBarrier& b) {
;     ...
;             const unsigned og = xb_add(&bar[XB_TOP], 1u);
;             const unsigned tg = og / nx;
;             if (og + 1u == (tg + 1u) * nx) xb_add(&bar[XB_TOPGEN], 1u);
;             else XB_SPIN(xb_ld(&bar[XB_TOPGEN]) == tg, bar);
.LBB0_961:
	s_or_b64 exec, exec, s[14:15]
	v_cvt_f32_u32_e32 v3, v0
	s_waitcnt vmcnt(0)
	v_readfirstlane_b32 s4, v2
	s_mov_b64 s[14:15], -1
	v_rcp_iflag_f32_e32 v3, v3
	v_add_u32_e32 v1, s4, v1
	v_add_u32_e32 v4, 1, v1
	v_mul_f32_e32 v2, 0x4f7ffffe, v3
	v_cvt_u32_f32_e32 v2, v2
	v_sub_u32_e32 v3, 0, v0
	v_mul_lo_u32 v3, v3, v2
	v_mul_hi_u32 v3, v2, v3
	v_add_u32_e32 v2, v2, v3
	v_mul_hi_u32 v2, v1, v2
	v_mul_lo_u32 v3, v2, v0
	v_sub_u32_e32 v1, v1, v3
	v_add_u32_e32 v5, 1, v2
	v_cmp_ge_u32_e32 vcc, v1, v0
	v_sub_u32_e32 v3, v1, v0
	s_nop 0
	v_cndmask_b32_e32 v2, v2, v5, vcc
	v_cndmask_b32_e32 v1, v1, v3, vcc
	v_add_u32_e32 v3, 1, v2
	v_cmp_ge_u32_e32 vcc, v1, v0
	s_nop 1
	v_cndmask_b32_e32 v2, v2, v3, vcc
	v_mul_lo_u32 v1, v0, v2
	v_add_u32_e32 v0, v1, v0
	v_cmp_ne_u32_e32 vcc, v4, v0
	v_mov_b64_e32 v[0:1], s[26:27]
	s_and_saveexec_b64 s[4:5], vcc
	s_cbranch_execz .LBB0_973
	v_mov_b32_e32 v0, 0
	global_load_dword v1, v0, s[26:27] sc1
	s_mov_b64 s[16:17], 0
	s_waitcnt vmcnt(0)
	v_cmp_eq_u32_e32 vcc, v1, v2
	s_and_saveexec_b64 s[14:15], vcc
	s_cbranch_execz .LBB0_972
	s_mov_b64 s[28:29], s[26:27]
	s_mov_b32 s26, 1
	global_load_dword v250, v0, s[28:29] sc1
	s_sleep 16
	global_load_dword v251, v0, s[28:29] sc1
	s_branch .LBB0_965

; __device__ __forceinline__ unsigned xb_ld(unsigned* p)              { return __hip_atomic_load(p, __ATOMIC_RELAXED, __HIP_MEMORY_SCOPE_AGENT); }
; #define XB_SPIN(cond, bar) do { unsigned _sp = 0; while (cond) { __builtin_amdgcn_s_sleep(1); \
;     if ((++_sp & 255u) == 0u) { if (xb_ld(&(bar)[XB_TMO])) break; if (_sp > XB_SPIN_CAP) { atomicAdd(&(bar)[XB_TMO], 1u); break; } } } } while (0)
; __device__ __forceinline__ void xcd_barrier(const XcdBarrier& b) {
;     ...
;             else XB_SPIN(xb_ld(&bar[XB_TOPGEN]) == tg, bar);
.LBB0_967:
	s_waitcnt vmcnt(1)
	v_mov_b32_e32 v1, v250
	v_cmp_ne_u32_e32 vcc, v1, v2
	s_nop 1
	s_cbranch_vccnz .Ldp13
	global_load_dword v250, v0, s[28:29] sc1
	s_waitcnt vmcnt(1)
	v_mov_b32_e32 v1, v251
	v_cmp_ne_u32_e32 vcc, v1, v2
	s_nop 1
	s_cbranch_vccnz .Ldp13
	global_load_dword v251, v0, s[28:29] sc1
.Ldp13:
	s_add_i32 s26, s26, 1
	s_mov_b64 s[20:21], -1
	v_cmp_ne_u32_e32 vcc, v1, v2
	s_orn2_b64 s[24:25], vcc, exec
	s_branch .LBB0_964
